# static priority raise for waves 4-7 also during ssd_s1 items only (not gmlp), reset at the m2 item-loop latch
# baseline (speedup 1.0000x reference)
.LBB0_616:
	s_setprio 0
	v_readlane_b32 s2, v243, 13
	s_add_i32 s96, s96, s2
	s_add_i32 s47, s47, s2
	v_readlane_b32 s2, v243, 54
	s_add_i32 s46, s46, s2
	s_cmpk_gt_i32 s96, 0x1ff
	s_cbranch_scc1 .LBB0_655
.LBB0_617:
	s_cmpk_gt_i32 s96, 0xff
	s_mov_b64 s[30:31], -1
	s_cbranch_scc0 .LBB0_635
	v_readfirstlane_b32 s4, v1
	s_bitcmp1_b32 s4, 8
	s_cbranch_scc0 .Ls1_prio_skip
	s_setprio 2
.Ls1_prio_skip:
	s_mov_b64 s[4:5], s[0:1]
	s_load_dwordx2 s[34:35], s[4:5], 0xd8
	s_mov_b64 s[4:5], s[0:1]
	s_load_dwordx2 s[62:63], s[4:5], 0xa0
	s_mov_b64 s[4:5], s[0:1]
	s_load_dwordx2 s[40:41], s[4:5], 0xa8
	s_add_i32 s4, s96, 0xffffff00
	s_mov_b64 s[70:71], s[0:1]
	s_and_b32 s55, s96, 1
	s_bfe_u32 s2, s96, 0x60001
	s_lshr_b32 s48, s4, 7
	s_and_saveexec_b64 s[30:31], s[6:7]
	s_cbranch_execz .LBB0_621
	s_load_dwordx2 s[50:51], s[70:71], 0xb8
	v_readlane_b32 s70, v242, 20
	s_lshl_b64 s[4:5], s[48:49], 14
	s_lshl_b32 s38, s2, 8
	v_readlane_b32 s71, v242, 21
	s_or_b32 s4, s4, s38
	s_lshl_b64 s[70:71], s[70:71], 2
	v_lshl_add_u32 v6, s55, 1, v60
	s_waitcnt lgkmcnt(0)
	s_add_u32 s50, s50, s70
	v_ashrrev_i32_e32 v7, 31, v6
	s_addc_u32 s51, s51, s71
	v_lshlrev_b64 v[2:3], 2, v[6:7]
	v_lshl_add_u64 v[4:5], s[50:51], 0, v[2:3]
	global_load_dword v4, v[4:5], off
	v_lshl_add_u64 v[12:13], s[34:35], 0, v[2:3]
	s_mov_b64 s[50:51], 0x16000000
	v_mov_b32_e32 v3, s5
	v_or_b32_e32 v2, s4, v62
	v_mov_b32_e32 v5, s5
	v_lshl_add_u64 v[14:15], v[12:13], 0, s[50:51]
	v_lshlrev_b64 v[16:17], 4, v[2:3]
	v_lshl_add_u64 v[2:3], v[14:15], 0, v[16:17]
	global_load_dword v2, v[2:3], off
	v_mov_b32_e32 v9, s5
	v_or_b32_e32 v8, s4, v68
	v_lshlrev_b64 v[8:9], 4, v[8:9]
	v_add_u32_e32 v22, -2, v208
	s_waitcnt vmcnt(1)
	v_mul_f32_e32 v4, 0x3fb8aa3b, v4
	v_exp_f32_e32 v25, v4
	v_or_b32_e32 v4, s4, v64
	v_lshlrev_b64 v[18:19], 4, v[4:5]
	v_lshl_add_u64 v[4:5], v[14:15], 0, v[18:19]
	global_load_dword v3, v[4:5], off
	v_mov_b32_e32 v5, s5
	v_or_b32_e32 v4, s4, v66
	v_lshlrev_b64 v[20:21], 4, v[4:5]
	v_lshl_add_u64 v[4:5], v[14:15], 0, v[20:21]
	global_load_dword v4, v[4:5], off
	v_lshl_add_u64 v[14:15], v[14:15], 0, v[8:9]
	global_load_dword v5, v[14:15], off
	v_and_b32_e32 v14, 64, v208
	v_add_u32_e32 v15, -1, v208
	v_cmp_lt_i32_e32 vcc, v15, v14
	s_mov_b64 s[4:5], 0x16080000
	v_lshl_add_u64 v[12:13], v[12:13], 0, s[4:5]
	v_cndmask_b32_e32 v15, v15, v208, vcc
	v_cmp_lt_i32_e32 vcc, v22, v14
	v_lshlrev_b32_e32 v15, 2, v15
	v_lshl_add_u64 v[18:19], v[12:13], 0, v[18:19]
	v_cndmask_b32_e32 v22, v22, v208, vcc
	v_lshlrev_b32_e32 v26, 2, v22
	v_add_u32_e32 v22, -4, v208
	v_cmp_lt_i32_e32 vcc, v22, v14
	v_lshl_add_u64 v[20:21], v[12:13], 0, v[20:21]
	s_nop 0
	v_cndmask_b32_e32 v22, v22, v208, vcc
	v_lshlrev_b32_e32 v27, 2, v22
	v_add_u32_e32 v22, -8, v208
	v_cmp_lt_i32_e32 vcc, v22, v14
	s_nop 1
	v_cndmask_b32_e32 v22, v22, v208, vcc
	v_lshlrev_b32_e32 v28, 2, v22
	v_add_u32_e32 v22, -16, v208
	v_cmp_lt_i32_e32 vcc, v22, v14
	s_nop 1
	v_cndmask_b32_e32 v22, v22, v208, vcc
	v_lshlrev_b32_e32 v29, 2, v22
	v_subrev_u32_e32 v22, 32, v208
	v_cmp_lt_i32_e32 vcc, v22, v14
	s_nop 1
	v_cndmask_b32_e32 v14, v22, v208, vcc
	v_lshl_add_u64 v[22:23], v[12:13], 0, v[16:17]
	s_waitcnt vmcnt(3)
	v_fma_f32 v16, -v25, v2, 0
	v_lshlrev_b32_e32 v14, 2, v14
	s_waitcnt vmcnt(2)
	v_fma_f32 v17, -v25, v3, v16
	s_waitcnt vmcnt(1)
	v_fma_f32 v24, -v25, v4, v17
	s_waitcnt vmcnt(0)
	v_fma_f32 v25, -v25, v5, v24
	ds_bpermute_b32 v15, v15, v25
	s_waitcnt lgkmcnt(0)
	v_add_f32_e32 v15, v25, v15
	v_cndmask_b32_e64 v15, v15, v25, s[8:9]
	ds_bpermute_b32 v26, v26, v15
	s_waitcnt lgkmcnt(0)
	v_add_f32_e32 v26, v15, v26
	v_cndmask_b32_e64 v15, v26, v15, s[10:11]
	ds_bpermute_b32 v26, v27, v15
	s_waitcnt lgkmcnt(0)
	v_add_f32_e32 v26, v15, v26
	v_cndmask_b32_e64 v15, v26, v15, s[12:13]
	ds_bpermute_b32 v26, v28, v15
	s_waitcnt lgkmcnt(0)
	v_add_f32_e32 v26, v15, v26
	v_cndmask_b32_e64 v15, v26, v15, s[14:15]
	ds_bpermute_b32 v26, v29, v15
	s_waitcnt lgkmcnt(0)
	v_add_f32_e32 v26, v15, v26
	v_cndmask_b32_e64 v15, v26, v15, s[16:17]
	ds_bpermute_b32 v14, v14, v15
	s_waitcnt lgkmcnt(0)
	v_add_f32_e32 v14, v15, v14
	v_cndmask_b32_e64 v15, v14, v15, s[18:19]
	v_sub_f32_e32 v26, v15, v25
	v_pk_add_f32 v[16:17], v[16:17], v[26:27] op_sel_hi:[1,0]
	global_store_dword v[22:23], v16, off
	global_store_dword v[18:19], v17, off
	v_pk_add_f32 v[18:19], v[24:25], v[26:27] op_sel_hi:[1,0]
	global_store_dword v[20:21], v18, off
	ds_write_b128 v65, v[16:19]
	ds_write_b128 v67, v[2:5]
	v_lshl_add_u64 v[2:3], v[12:13], 0, v[8:9]
	global_store_dword v[2:3], v19, off
	s_and_b64 exec, exec, s[20:21]
	s_cbranch_execz .LBB0_621
	s_lshl_b64 s[4:5], s[48:49], 10
	s_add_u32 s4, s34, s4
	s_addc_u32 s5, s35, s5
	s_lshl_b32 s38, s2, 4
	s_add_u32 s4, s4, s38
	s_addc_u32 s5, s5, 0
	v_lshl_add_u64 v[2:3], v[6:7], 2, s[4:5]
	v_add_co_u32_e32 v2, vcc, 0xc0000, v2
	s_nop 1
	v_addc_co_u32_e32 v3, vcc, 0, v3, vcc
	global_store_dword v[2:3], v14, off
